# grid barrier: last local arriver adds to the cross-XCC counter without waiting; all workgroups poll that counter (no release word)
# speedup vs baseline: 1.0168x; 1.0168x over previous
.LBB0_590:
	v_readlane_b32 s4, v251, 10
	v_readlane_b32 s5, v251, 11
	v_cvt_f32_u32_e32 v1, v3
	v_sub_u32_e32 v5, 0, v3
	v_rcp_iflag_f32_e32 v1, v1
	s_nop 1
	global_atomic_add v4, v131, v220, s[4:5] sc0
	v_mul_f32_e32 v1, 0x4f7ffffe, v1
	v_cvt_u32_f32_e32 v1, v1
	v_mul_lo_u32 v5, v5, v1
	v_mul_hi_u32 v5, v1, v5
	v_add_u32_e32 v1, v1, v5
	s_waitcnt vmcnt(0)
	v_mul_hi_u32 v1, v4, v1
	v_mul_lo_u32 v5, v1, v3
	v_sub_u32_e32 v5, v4, v5
	v_add_u32_e32 v6, 1, v1
	v_cmp_ge_u32_e32 vcc, v5, v3
	v_add_u32_e32 v4, 1, v4
	s_nop 0
	v_cndmask_b32_e32 v1, v1, v6, vcc
	v_sub_u32_e32 v6, v5, v3
	v_cndmask_b32_e32 v5, v5, v6, vcc
	v_add_u32_e32 v6, 1, v1
	v_cmp_ge_u32_e32 vcc, v5, v3
	s_nop 1
	v_cndmask_b32_e32 v1, v1, v6, vcc
	v_mul_lo_u32 v5, v3, v1
	v_add_u32_e32 v3, v5, v3
	v_cmp_ne_u32_e32 vcc, v4, v3
	s_waitcnt lgkmcnt(0)
	v_mad_u32_u24 v6, v1, v2, v2
	v_readlane_b32 s4, v251, 14
	v_readlane_b32 s5, v251, 15
	s_mov_b32 s7, 0
	s_nop 4
	s_cbranch_vccnz .Lxb2_poll
	global_atomic_add v131, v220, s[4:5]
.Lxb2_poll:
	global_load_dword v2, v131, s[4:5] sc1
	s_add_i32 s7, s7, 1
	s_waitcnt vmcnt(0)
	v_cmp_lt_u32_e32 vcc, v2, v6
	s_nop 1
	s_cbranch_vccz .Lxb2_done
	s_sleep 1
	s_cmp_lt_u32 s7, 0x4000
	s_cbranch_scc1 .Lxb2_poll
